# hand-written bf16-row GEMM epilogue: coalesced stores via lane permute, rowss prefetch, counted waits at tile boundary
# speedup vs baseline: 1.0086x; 1.0086x over previous
.LBB0_390:
	s_xor_b64 s[50:51], s[6:7], -1
	v_readlane_b32 s6, v241, 0
	v_readlane_b32 s7, v241, 1
	s_xor_b64 s[58:59], s[6:7], -1
	s_ashr_i32 s27, s26, 31
	s_cmp_lg_u64 s[8:9], 0
	s_cselect_b64 s[64:65], -1, 0
	s_and_b32 s6, s29, 3
	s_add_i32 m0, s41, 0x18000
	v_lshl_add_u64 v[6:7], v[6:7], 0, s[86:87]
	s_lshl_b32 s84, s1, 6
	s_lshl_b32 s1, s1, 13
	s_lshl_b32 s85, s6, 5
	s_lshl_b32 s11, s6, 12
	s_waitcnt vmcnt(2)
	s_barrier
	global_load_lds_dwordx4 v[6:7], off
	v_lshl_add_u64 v[4:5], v[4:5], 0, s[86:87]
	s_add_i32 m0, s41, 0x1a000
	s_add_i32 s89, s41, 0x8000
	s_add_i32 s92, s41, 0xa000
	global_load_lds_dwordx4 v[4:5], off
	v_lshl_add_u64 v[0:1], v[0:1], 0, s[86:87]
	s_mov_b32 m0, s89
	s_add_u32 s6, s14, 0x40080
	global_load_lds_dwordx4 v[0:1], off
	v_lshl_add_u64 v[0:1], v[2:3], 0, s[86:87]
	s_mov_b32 m0, s92
	s_addc_u32 s7, s15, 0
	global_load_lds_dwordx4 v[0:1], off
	s_add_i32 m0, s41, 0x1c000
	v_lshl_add_u64 v[0:1], s[6:7], 0, v[132:133]
	global_load_lds_dwordx4 v[0:1], off
	v_lshl_add_u64 v[0:1], s[6:7], 0, v[136:137]
	s_add_i32 m0, s41, 0x1e000
	v_and_b32_e32 v139, 15, v224
	global_load_lds_dwordx4 v[0:1], off
	v_bfe_u32 v0, v224, 4, 2
	v_lshlrev_b32_e32 v1, 6, v139
	v_lshlrev_b32_e32 v2, 2, v224
	v_lshlrev_b32_e32 v138, 3, v0
	v_lshl_or_b32 v1, v0, 4, v1
	v_and_b32_e32 v2, 32, v2
	v_or_b32_e32 v0, v0, v139
	v_cmp_eq_u32_e64 s[6:7], 0, v0
	v_bitop3_b32 v0, v1, s1, v2 bitop3:0xde
	v_bitop3_b32 v154, s11, v1, v2 bitop3:0xf6
	v_cvt_f32_u32_e32 v1, s35
	v_mul_f32_e32 v2, 0x4f7ffffe, v8
	s_cmpk_lt_u32 s28, 0x100
	v_cvt_u32_f32_e32 v2, v2
	v_rcp_iflag_f32_e32 v1, v1
	s_cselect_b64 s[70:71], -1, 0
	s_lshr_b32 s1, s28, 4
	s_bfe_u32 s94, s29, 0x10001
	s_and_b32 s1, s1, 4
	v_mul_f32_e32 v1, 0x4f7ffffe, v1
	s_add_u32 s95, s8, s1
	v_cvt_u32_f32_e32 v1, v1
	s_addc_u32 s98, s9, 0
	s_sub_i32 s1, 0, s5
	v_readfirstlane_b32 s8, v2
	s_mul_i32 s1, s1, s8
	s_mul_hi_u32 s1, s8, s1
	s_add_i32 s99, s8, s1
	v_readfirstlane_b32 s8, v1
	v_lshlrev_b32_e32 v1, 14, v9
	v_and_b32_e32 v1, 0xffff8000, v1
	v_lshl_add_u32 v1, v10, 11, v1
	v_and_b32_e32 v2, 1, v9
	v_lshl_or_b32 v1, v2, 6, v1
	v_lshl_add_u32 v140, v11, 1, v1
	v_lshlrev_b32_e32 v1, 14, v12
	s_sub_i32 s1, 0, s35
	v_and_b32_e32 v1, 0xffff8000, v1
	s_mul_i32 s1, s1, s8
	v_lshl_add_u32 v1, v13, 11, v1
	v_and_b32_e32 v2, 1, v12
	s_mul_hi_u32 s1, s8, s1
	v_lshl_or_b32 v1, v2, 6, v1
	s_mov_b32 s93, 0
	v_or_b32_e32 v155, s85, v138
	s_add_i32 s52, s8, s1
	v_mov_b32_e32 v141, v101
	v_lshl_add_u32 v142, v14, 1, v1
	v_mov_b32_e32 v143, v101
	v_add_u32_e32 v156, 0, v0
	s_add_u32 s30, s12, 0x40080
	s_addc_u32 s31, s13, 0
	v_lshl_add_u64 v[0:1], s[30:31], 0, v[140:141]
	s_add_i32 m0, s41, 0xc000
	s_nop 0
	global_load_lds_dwordx4 v[0:1], off
	v_lshl_add_u64 v[0:1], s[30:31], 0, v[142:143]
	s_add_i32 m0, s41, 0xe000
	s_nop 0
	global_load_lds_dwordx4 v[0:1], off
	s_waitcnt vmcnt(0)
	s_barrier
	s_branch .LBB0_393

.LBB0_395:
	s_lshl_b32 s1, s40, 8
	s_add_i32 s1, s1, s84
	v_or_b32_e32 v152, s1, v139
	v_lshlrev_b32_e32 v152, 2, v152
	global_load_dword v236, v152, s[66:67]
	global_load_dword v237, v152, s[66:67] offset:64
	global_load_dword v238, v152, s[66:67] offset:128
	global_load_dword v239, v152, s[66:67] offset:192
	global_load_dword v240, v152, s[66:67] offset:512
	global_load_dword v244, v152, s[66:67] offset:576
	global_load_dword v245, v152, s[66:67] offset:640
	global_load_dword v246, v152, s[66:67] offset:704
	s_ashr_i32 s75, s74, 31
	s_lshl_b64 s[28:29], s[74:75], 19
	s_add_u32 s76, s62, s28
	s_addc_u32 s77, s63, s29
	s_and_b64 s[28:29], s[8:9], exec
	s_cselect_b32 s11, s77, s13
	s_cselect_b32 s30, s76, s12
	s_ashr_i32 s73, s72, 31
	s_lshl_b64 s[28:29], s[72:73], 19
	s_add_u32 s78, s20, s28
	s_addc_u32 s79, s21, s29
	s_and_b64 s[28:29], s[8:9], exec
	s_cselect_b32 s31, s79, s15
	s_cselect_b32 s47, s78, s14
	s_add_u32 s12, s12, 0x40080
	s_addc_u32 s13, s13, 0
	s_add_u32 s54, s14, 0x100
	v_mov_b32_e32 v0, 0
	s_addc_u32 s55, s15, 0
	s_mov_b32 s73, -2
	v_mov_b32_e32 v1, v0
	v_mov_b32_e32 v2, v0
	v_mov_b32_e32 v3, v0
	v_mov_b32_e32 v4, v0
	v_mov_b32_e32 v5, v0
	v_mov_b32_e32 v6, v0
	v_mov_b32_e32 v7, v0
	v_mov_b32_e32 v16, v0
	v_mov_b32_e32 v17, v0
	v_mov_b32_e32 v18, v0
	v_mov_b32_e32 v19, v0
	v_mov_b32_e32 v20, v0
	v_mov_b32_e32 v21, v0
	v_mov_b32_e32 v22, v0
	v_mov_b32_e32 v23, v0
	v_mov_b32_e32 v32, v0
	v_mov_b32_e32 v33, v0
	v_mov_b32_e32 v34, v0
	v_mov_b32_e32 v35, v0
	v_mov_b32_e32 v36, v0
	v_mov_b32_e32 v37, v0
	v_mov_b32_e32 v38, v0
	v_mov_b32_e32 v39, v0
	v_mov_b32_e32 v48, v0
	v_mov_b32_e32 v49, v0
	v_mov_b32_e32 v50, v0
	v_mov_b32_e32 v51, v0
	v_mov_b32_e32 v52, v0
	v_mov_b32_e32 v53, v0
	v_mov_b32_e32 v54, v0
	v_mov_b32_e32 v55, v0
	v_mov_b32_e32 v8, v0
	v_mov_b32_e32 v9, v0
	v_mov_b32_e32 v10, v0
	v_mov_b32_e32 v11, v0
	v_mov_b32_e32 v12, v0
	v_mov_b32_e32 v13, v0
	v_mov_b32_e32 v14, v0
	v_mov_b32_e32 v15, v0
	v_mov_b32_e32 v24, v0
	v_mov_b32_e32 v25, v0
	v_mov_b32_e32 v26, v0
	v_mov_b32_e32 v27, v0
	v_mov_b32_e32 v28, v0
	v_mov_b32_e32 v29, v0
	v_mov_b32_e32 v30, v0
	v_mov_b32_e32 v31, v0
	v_mov_b32_e32 v40, v0
	v_mov_b32_e32 v41, v0
	v_mov_b32_e32 v42, v0
	v_mov_b32_e32 v43, v0
	v_mov_b32_e32 v44, v0
	v_mov_b32_e32 v45, v0
	v_mov_b32_e32 v46, v0
	v_mov_b32_e32 v47, v0
	v_mov_b32_e32 v56, v0
	v_mov_b32_e32 v57, v0
	v_mov_b32_e32 v58, v0
	v_mov_b32_e32 v59, v0
	v_mov_b32_e32 v60, v0
	v_mov_b32_e32 v61, v0
	v_mov_b32_e32 v62, v0
	v_mov_b32_e32 v63, v0
	v_mov_b32_e32 v64, v0
	v_mov_b32_e32 v65, v0
	v_mov_b32_e32 v66, v0
	v_mov_b32_e32 v67, v0
	v_mov_b32_e32 v68, v0
	v_mov_b32_e32 v69, v0
	v_mov_b32_e32 v70, v0
	v_mov_b32_e32 v71, v0
	v_mov_b32_e32 v80, v0
	v_mov_b32_e32 v81, v0
	v_mov_b32_e32 v82, v0
	v_mov_b32_e32 v83, v0
	v_mov_b32_e32 v84, v0
	v_mov_b32_e32 v85, v0
	v_mov_b32_e32 v86, v0
	v_mov_b32_e32 v87, v0
	v_mov_b32_e32 v96, v0
	v_mov_b32_e32 v97, v0
	v_mov_b32_e32 v98, v0
	v_mov_b32_e32 v99, v0
	v_mov_b32_e32 v102, v0
	v_mov_b32_e32 v103, v0
	v_mov_b32_e32 v104, v0
	v_mov_b32_e32 v105, v0
	v_mov_b32_e32 v114, v0
	v_mov_b32_e32 v115, v0
	v_mov_b32_e32 v116, v0
	v_mov_b32_e32 v117, v0
	v_mov_b32_e32 v118, v0
	v_mov_b32_e32 v119, v0
	v_mov_b32_e32 v120, v0
	v_mov_b32_e32 v121, v0
	v_mov_b32_e32 v72, v0
	v_mov_b32_e32 v73, v0
	v_mov_b32_e32 v74, v0
	v_mov_b32_e32 v75, v0
	v_mov_b32_e32 v76, v0
	v_mov_b32_e32 v77, v0
	v_mov_b32_e32 v78, v0
	v_mov_b32_e32 v79, v0
	v_mov_b32_e32 v88, v0
	v_mov_b32_e32 v89, v0
	v_mov_b32_e32 v90, v0
	v_mov_b32_e32 v91, v0
	v_mov_b32_e32 v92, v0
	v_mov_b32_e32 v93, v0
	v_mov_b32_e32 v94, v0
	v_mov_b32_e32 v95, v0
	v_mov_b32_e32 v106, v0
	v_mov_b32_e32 v107, v0
	v_mov_b32_e32 v108, v0
	v_mov_b32_e32 v109, v0
	v_mov_b32_e32 v110, v0
	v_mov_b32_e32 v111, v0
	v_mov_b32_e32 v112, v0
	v_mov_b32_e32 v113, v0
	v_mov_b32_e32 v122, v0
	v_mov_b32_e32 v123, v0
	v_mov_b32_e32 v124, v0
	v_mov_b32_e32 v125, v0
	v_mov_b32_e32 v126, v0
	v_mov_b32_e32 v127, v0
	v_mov_b32_e32 v128, v0
	v_mov_b32_e32 v129, v0
.LBB0_396:
	s_add_u32 s1, s12, 0xfffc0080
	s_addc_u32 s14, s13, -1
	s_add_i32 s33, 0, 0x10000
	s_cmp_eq_u32 s73, 12
	s_cselect_b32 s29, s11, s14
	s_cselect_b32 s28, s30, s1
	v_add_u32_e32 v100, s33, v154
	s_cselect_b32 s15, s31, s55
	s_cselect_b32 s14, s47, s54
	s_add_i32 s1, 0, 0x14000
	ds_read_b128 v[144:147], v100
	ds_read_b128 v[148:151], v100 offset:1024
	ds_read_b128 v[158:161], v100 offset:2048
	ds_read_b128 v[162:165], v100 offset:3072
	v_add_u32_e32 v100, s1, v154
	ds_read_b128 v[166:169], v100
	ds_read_b128 v[170:173], v100 offset:1024
	ds_read_b128 v[174:177], v100 offset:2048
	ds_read_b128 v[178:181], v100 offset:3072
	ds_read_b128 v[182:185], v156
	ds_read_b128 v[186:189], v156 offset:1024
	ds_read_b128 v[190:193], v156 offset:2048
	ds_read_b128 v[194:197], v156 offset:3072
	ds_read_b128 v[198:201], v156 offset:4096
	ds_read_b128 v[202:205], v156 offset:5120
	ds_read_b128 v[208:211], v156 offset:6144
	ds_read_b128 v[226:229], v156 offset:7168
	s_cmp_eq_u32 s73, -2
	s_cbranch_scc1 .Lmy_b16_sp1first
	v_lshl_add_u64 v[152:153], s[12:13], 0, v[140:141]
	s_add_i32 m0, s41, 0xc000
	s_nop 0
	global_load_lds_dwordx4 v[152:153], off
	v_lshl_add_u64 v[152:153], s[12:13], 0, v[142:143]
	s_add_i32 m0, s41, 0xe000
	s_nop 0
	global_load_lds_dwordx4 v[152:153], off
	s_waitcnt vmcnt(8)
	s_branch .Lmy_b16_sp1join
.Lmy_b16_sp1first:
	s_waitcnt vmcnt(32)
.Lmy_b16_sp1join:
	s_waitcnt lgkmcnt(0)
	s_barrier
	s_setprio 1
	s_waitcnt lgkmcnt(0)
	v_mfma_f32_16x16x32_bf16 v[126:129], v[144:147], v[182:185], v[126:129]
	v_mfma_f32_16x16x32_bf16 v[122:125], v[158:161], v[182:185], v[122:125]
	v_mfma_f32_16x16x32_bf16 v[110:113], v[144:147], v[190:193], v[110:113]
	v_mfma_f32_16x16x32_bf16 v[106:109], v[158:161], v[190:193], v[106:109]
	v_mfma_f32_16x16x32_bf16 v[92:95], v[144:147], v[198:201], v[92:95]
	v_mfma_f32_16x16x32_bf16 v[88:91], v[158:161], v[198:201], v[88:91]
	v_mfma_f32_16x16x32_bf16 v[76:79], v[144:147], v[208:211], v[76:79]
	v_mfma_f32_16x16x32_bf16 v[72:75], v[158:161], v[208:211], v[72:75]
	v_mfma_f32_16x16x32_bf16 v[126:129], v[148:151], v[186:189], v[126:129]
	v_mfma_f32_16x16x32_bf16 v[122:125], v[162:165], v[186:189], v[122:125]
	v_mfma_f32_16x16x32_bf16 v[110:113], v[148:151], v[194:197], v[110:113]
	v_mfma_f32_16x16x32_bf16 v[106:109], v[162:165], v[194:197], v[106:109]
	v_mfma_f32_16x16x32_bf16 v[92:95], v[148:151], v[202:205], v[92:95]
	v_mfma_f32_16x16x32_bf16 v[88:91], v[162:165], v[202:205], v[88:91]
	v_mfma_f32_16x16x32_bf16 v[76:79], v[148:151], v[226:229], v[76:79]
	v_mfma_f32_16x16x32_bf16 v[72:75], v[162:165], v[226:229], v[72:75]
	s_setprio 0
	s_setprio 1
	v_mfma_f32_16x16x32_bf16 v[118:121], v[166:169], v[182:185], v[118:121]
	v_mfma_f32_16x16x32_bf16 v[114:117], v[174:177], v[182:185], v[114:117]
	v_mfma_f32_16x16x32_bf16 v[102:105], v[166:169], v[190:193], v[102:105]
	v_mfma_f32_16x16x32_bf16 v[96:99], v[174:177], v[190:193], v[96:99]
	v_mfma_f32_16x16x32_bf16 v[84:87], v[166:169], v[198:201], v[84:87]
	v_mfma_f32_16x16x32_bf16 v[80:83], v[174:177], v[198:201], v[80:83]
	v_mfma_f32_16x16x32_bf16 v[68:71], v[166:169], v[208:211], v[68:71]
	v_mfma_f32_16x16x32_bf16 v[64:67], v[174:177], v[208:211], v[64:67]
	v_mfma_f32_16x16x32_bf16 v[118:121], v[170:173], v[186:189], v[118:121]
	v_mfma_f32_16x16x32_bf16 v[114:117], v[178:181], v[186:189], v[114:117]
	v_mfma_f32_16x16x32_bf16 v[102:105], v[170:173], v[194:197], v[102:105]
	v_mfma_f32_16x16x32_bf16 v[96:99], v[178:181], v[194:197], v[96:99]
	v_mfma_f32_16x16x32_bf16 v[84:87], v[170:173], v[202:205], v[84:87]
	v_mfma_f32_16x16x32_bf16 v[80:83], v[178:181], v[202:205], v[80:83]
	v_mfma_f32_16x16x32_bf16 v[68:71], v[170:173], v[226:229], v[68:71]
	v_mfma_f32_16x16x32_bf16 v[64:67], v[178:181], v[226:229], v[64:67]
	s_setprio 0
	s_barrier
	s_add_i32 s33, s33, s34
	v_lshl_add_u64 v[152:153], s[14:15], 0, v[132:133]
	s_mov_b32 m0, s33
	ds_read_b128 v[182:185], v156 offset:16384
	ds_read_b128 v[186:189], v156 offset:17408
	ds_read_b128 v[190:193], v156 offset:18432
	ds_read_b128 v[194:197], v156 offset:19456
	ds_read_b128 v[198:201], v156 offset:20480
	ds_read_b128 v[202:205], v156 offset:21504
	ds_read_b128 v[208:211], v156 offset:22528
	ds_read_b128 v[226:229], v156 offset:23552
	global_load_lds_dwordx4 v[152:153], off
	s_add_i32 m0, s33, 0x2000
	s_add_u32 s80, s14, 0x40000
	v_lshl_add_u64 v[212:213], s[14:15], 0, v[136:137]
	s_addc_u32 s81, s15, 0
	s_add_i32 s1, s1, s34
	global_load_lds_dwordx4 v[212:213], off
	v_lshl_add_u64 v[230:231], s[80:81], 0, v[132:133]
	s_mov_b32 m0, s1
	v_lshl_add_u64 v[232:233], s[28:29], 0, v[134:135]
	global_load_lds_dwordx4 v[230:231], off
	v_lshl_add_u64 v[230:231], s[80:81], 0, v[136:137]
	s_add_i32 m0, s1, 0x2000
	s_nop 0
	global_load_lds_dwordx4 v[230:231], off
	v_lshl_add_u64 v[230:231], s[28:29], 0, v[130:131]
	s_mov_b32 m0, s41
	s_nop 0
	global_load_lds_dwordx4 v[230:231], off
	s_mov_b32 m0, s60
	s_nop 0
	global_load_lds_dwordx4 v[232:233], off
	s_cmp_eq_u32 s73, -2
	s_cbranch_scc1 .Lmy_b16_w2first
	s_waitcnt vmcnt(8)
	s_branch .Lmy_b16_w2join

.Lmy_b16_w2join:
	s_waitcnt lgkmcnt(0)
	s_barrier
	s_setprio 1
	s_waitcnt lgkmcnt(0)
	v_mfma_f32_16x16x32_bf16 v[60:63], v[144:147], v[182:185], v[60:63]
	v_mfma_f32_16x16x32_bf16 v[56:59], v[158:161], v[182:185], v[56:59]
	v_mfma_f32_16x16x32_bf16 v[44:47], v[144:147], v[190:193], v[44:47]
	v_mfma_f32_16x16x32_bf16 v[40:43], v[158:161], v[190:193], v[40:43]
	v_mfma_f32_16x16x32_bf16 v[28:31], v[144:147], v[198:201], v[28:31]
	v_mfma_f32_16x16x32_bf16 v[24:27], v[158:161], v[198:201], v[24:27]
	v_mfma_f32_16x16x32_bf16 v[12:15], v[144:147], v[208:211], v[12:15]
	v_mfma_f32_16x16x32_bf16 v[8:11], v[158:161], v[208:211], v[8:11]
	v_mfma_f32_16x16x32_bf16 v[60:63], v[148:151], v[186:189], v[60:63]
	v_mfma_f32_16x16x32_bf16 v[56:59], v[162:165], v[186:189], v[56:59]
	v_mfma_f32_16x16x32_bf16 v[44:47], v[148:151], v[194:197], v[44:47]
	v_mfma_f32_16x16x32_bf16 v[40:43], v[162:165], v[194:197], v[40:43]
	v_mfma_f32_16x16x32_bf16 v[28:31], v[148:151], v[202:205], v[28:31]
	v_mfma_f32_16x16x32_bf16 v[24:27], v[162:165], v[202:205], v[24:27]
	v_mfma_f32_16x16x32_bf16 v[12:15], v[148:151], v[226:229], v[12:15]
	v_mfma_f32_16x16x32_bf16 v[8:11], v[162:165], v[226:229], v[8:11]
	s_setprio 0
	s_setprio 1
	v_mfma_f32_16x16x32_bf16 v[52:55], v[166:169], v[182:185], v[52:55]
	v_mfma_f32_16x16x32_bf16 v[48:51], v[174:177], v[182:185], v[48:51]
	v_mfma_f32_16x16x32_bf16 v[36:39], v[166:169], v[190:193], v[36:39]
	v_mfma_f32_16x16x32_bf16 v[32:35], v[174:177], v[190:193], v[32:35]
	v_mfma_f32_16x16x32_bf16 v[20:23], v[166:169], v[198:201], v[20:23]
	v_mfma_f32_16x16x32_bf16 v[16:19], v[174:177], v[198:201], v[16:19]
	v_mfma_f32_16x16x32_bf16 v[4:7], v[166:169], v[208:211], v[4:7]
	v_mfma_f32_16x16x32_bf16 v[0:3], v[174:177], v[208:211], v[0:3]
	v_mfma_f32_16x16x32_bf16 v[52:55], v[170:173], v[186:189], v[52:55]
	v_mfma_f32_16x16x32_bf16 v[48:51], v[178:181], v[186:189], v[48:51]
	v_mfma_f32_16x16x32_bf16 v[36:39], v[170:173], v[194:197], v[36:39]
	v_mfma_f32_16x16x32_bf16 v[32:35], v[178:181], v[194:197], v[32:35]
	v_mfma_f32_16x16x32_bf16 v[20:23], v[170:173], v[202:205], v[20:23]
	v_mfma_f32_16x16x32_bf16 v[16:19], v[178:181], v[202:205], v[16:19]
	v_mfma_f32_16x16x32_bf16 v[4:7], v[170:173], v[226:229], v[4:7]
	v_mfma_f32_16x16x32_bf16 v[0:3], v[178:181], v[226:229], v[0:3]
	s_setprio 0
	s_barrier
	s_add_i32 s1, 0, 0x18000
	v_add_u32_e32 v100, s1, v154
	s_add_i32 s33, 0, 0x1c000
	ds_read_b128 v[144:147], v100
	ds_read_b128 v[148:151], v100 offset:1024
	ds_read_b128 v[158:161], v100 offset:2048
	ds_read_b128 v[162:165], v100 offset:3072
	v_add_u32_e32 v100, s33, v154
	ds_read_b128 v[166:169], v100
	ds_read_b128 v[170:173], v100 offset:1024
	ds_read_b128 v[174:177], v100 offset:2048
	ds_read_b128 v[178:181], v100 offset:3072
	s_add_u32 s28, s28, 0x40000
	s_addc_u32 s29, s29, 0
	s_mov_b32 m0, s61
	v_lshl_add_u64 v[234:235], s[28:29], 0, v[130:131]
	ds_read_b128 v[182:185], v156 offset:32768
	ds_read_b128 v[186:189], v156 offset:33792
	ds_read_b128 v[190:193], v156 offset:34816
	ds_read_b128 v[194:197], v156 offset:35840
	ds_read_b128 v[198:201], v156 offset:36864
	ds_read_b128 v[202:205], v156 offset:37888
	ds_read_b128 v[208:211], v156 offset:38912
	ds_read_b128 v[226:229], v156 offset:39936
	global_load_lds_dwordx4 v[234:235], off
	v_lshl_add_u64 v[234:235], s[28:29], 0, v[134:135]
	s_mov_b32 m0, s69
	s_nop 0
	global_load_lds_dwordx4 v[234:235], off
	s_cmp_eq_u32 s73, -2
	s_cbranch_scc1 .Lmy_b16_w3first
	s_waitcnt vmcnt(8)
	s_branch .Lmy_b16_w3join

.Lmy_b16_w3join:
	s_waitcnt lgkmcnt(0)
	s_barrier
	s_setprio 1
	s_waitcnt lgkmcnt(0)
	v_mfma_f32_16x16x32_bf16 v[126:129], v[144:147], v[182:185], v[126:129]
	v_mfma_f32_16x16x32_bf16 v[122:125], v[158:161], v[182:185], v[122:125]
	v_mfma_f32_16x16x32_bf16 v[110:113], v[144:147], v[190:193], v[110:113]
	v_mfma_f32_16x16x32_bf16 v[106:109], v[158:161], v[190:193], v[106:109]
	v_mfma_f32_16x16x32_bf16 v[92:95], v[144:147], v[198:201], v[92:95]
	v_mfma_f32_16x16x32_bf16 v[88:91], v[158:161], v[198:201], v[88:91]
	v_mfma_f32_16x16x32_bf16 v[76:79], v[144:147], v[208:211], v[76:79]
	v_mfma_f32_16x16x32_bf16 v[72:75], v[158:161], v[208:211], v[72:75]
	v_mfma_f32_16x16x32_bf16 v[126:129], v[148:151], v[186:189], v[126:129]
	v_mfma_f32_16x16x32_bf16 v[122:125], v[162:165], v[186:189], v[122:125]
	v_mfma_f32_16x16x32_bf16 v[110:113], v[148:151], v[194:197], v[110:113]
	v_mfma_f32_16x16x32_bf16 v[106:109], v[162:165], v[194:197], v[106:109]
	v_mfma_f32_16x16x32_bf16 v[92:95], v[148:151], v[202:205], v[92:95]
	v_mfma_f32_16x16x32_bf16 v[88:91], v[162:165], v[202:205], v[88:91]
	v_mfma_f32_16x16x32_bf16 v[76:79], v[148:151], v[226:229], v[76:79]
	v_mfma_f32_16x16x32_bf16 v[72:75], v[162:165], v[226:229], v[72:75]
	s_setprio 0
	s_setprio 1
	v_mfma_f32_16x16x32_bf16 v[118:121], v[166:169], v[182:185], v[118:121]
	v_mfma_f32_16x16x32_bf16 v[114:117], v[174:177], v[182:185], v[114:117]
	v_mfma_f32_16x16x32_bf16 v[102:105], v[166:169], v[190:193], v[102:105]
	v_mfma_f32_16x16x32_bf16 v[96:99], v[174:177], v[190:193], v[96:99]
	v_mfma_f32_16x16x32_bf16 v[84:87], v[166:169], v[198:201], v[84:87]
	v_mfma_f32_16x16x32_bf16 v[80:83], v[174:177], v[198:201], v[80:83]
	v_mfma_f32_16x16x32_bf16 v[68:71], v[166:169], v[208:211], v[68:71]
	v_mfma_f32_16x16x32_bf16 v[64:67], v[174:177], v[208:211], v[64:67]
	v_mfma_f32_16x16x32_bf16 v[118:121], v[170:173], v[186:189], v[118:121]
	v_mfma_f32_16x16x32_bf16 v[114:117], v[178:181], v[186:189], v[114:117]
	v_mfma_f32_16x16x32_bf16 v[102:105], v[170:173], v[194:197], v[102:105]
	v_mfma_f32_16x16x32_bf16 v[96:99], v[178:181], v[194:197], v[96:99]
	v_mfma_f32_16x16x32_bf16 v[84:87], v[170:173], v[202:205], v[84:87]
	v_mfma_f32_16x16x32_bf16 v[80:83], v[178:181], v[202:205], v[80:83]
	v_mfma_f32_16x16x32_bf16 v[68:71], v[170:173], v[226:229], v[68:71]
	v_mfma_f32_16x16x32_bf16 v[64:67], v[178:181], v[226:229], v[64:67]
	s_setprio 0
	s_barrier
	s_add_i32 s1, s1, s34
	v_lshl_add_u64 v[152:153], v[152:153], 0, s[86:87]
	s_mov_b32 m0, s1
	ds_read_b128 v[182:185], v156 offset:49152
	ds_read_b128 v[186:189], v156 offset:50176
	ds_read_b128 v[190:193], v156 offset:51200
	ds_read_b128 v[194:197], v156 offset:52224
	ds_read_b128 v[198:201], v156 offset:53248
	ds_read_b128 v[202:205], v156 offset:54272
	ds_read_b128 v[208:211], v156 offset:55296
	ds_read_b128 v[226:229], v156 offset:56320
	global_load_lds_dwordx4 v[152:153], off
	s_add_i32 m0, s1, 0x2000
	s_add_u32 s14, s14, 0x40080
	v_lshl_add_u64 v[152:153], v[212:213], 0, s[86:87]
	s_addc_u32 s15, s15, 0
	s_add_i32 s1, s33, s34
	global_load_lds_dwordx4 v[152:153], off
	v_lshl_add_u64 v[152:153], s[14:15], 0, v[132:133]
	s_mov_b32 m0, s1
	s_nop 0
	global_load_lds_dwordx4 v[152:153], off
	v_lshl_add_u64 v[152:153], s[14:15], 0, v[136:137]
	s_add_i32 m0, s1, 0x2000
	s_nop 0
	global_load_lds_dwordx4 v[152:153], off
	v_lshl_add_u64 v[152:153], v[230:231], 0, s[86:87]
	s_mov_b32 m0, s89
	s_nop 0
	global_load_lds_dwordx4 v[152:153], off
	v_lshl_add_u64 v[152:153], v[232:233], 0, s[86:87]
	s_mov_b32 m0, s92
	s_nop 0
	global_load_lds_dwordx4 v[152:153], off
	s_waitcnt vmcnt(8)
	s_waitcnt lgkmcnt(0)
	s_barrier
	s_setprio 1
	s_waitcnt lgkmcnt(0)
	v_mfma_f32_16x16x32_bf16 v[60:63], v[144:147], v[182:185], v[60:63]
	v_mfma_f32_16x16x32_bf16 v[56:59], v[158:161], v[182:185], v[56:59]
	v_mfma_f32_16x16x32_bf16 v[44:47], v[144:147], v[190:193], v[44:47]
	v_mfma_f32_16x16x32_bf16 v[40:43], v[158:161], v[190:193], v[40:43]
	v_mfma_f32_16x16x32_bf16 v[28:31], v[144:147], v[198:201], v[28:31]
	v_mfma_f32_16x16x32_bf16 v[24:27], v[158:161], v[198:201], v[24:27]
	v_mfma_f32_16x16x32_bf16 v[12:15], v[144:147], v[208:211], v[12:15]
	v_mfma_f32_16x16x32_bf16 v[8:11], v[158:161], v[208:211], v[8:11]
	v_mfma_f32_16x16x32_bf16 v[60:63], v[148:151], v[186:189], v[60:63]
	v_mfma_f32_16x16x32_bf16 v[56:59], v[162:165], v[186:189], v[56:59]
	v_mfma_f32_16x16x32_bf16 v[44:47], v[148:151], v[194:197], v[44:47]
	v_mfma_f32_16x16x32_bf16 v[40:43], v[162:165], v[194:197], v[40:43]
	v_mfma_f32_16x16x32_bf16 v[28:31], v[148:151], v[202:205], v[28:31]
	v_mfma_f32_16x16x32_bf16 v[24:27], v[162:165], v[202:205], v[24:27]
	v_mfma_f32_16x16x32_bf16 v[12:15], v[148:151], v[226:229], v[12:15]
	v_mfma_f32_16x16x32_bf16 v[8:11], v[162:165], v[226:229], v[8:11]
	s_setprio 0
	s_setprio 1
	v_mfma_f32_16x16x32_bf16 v[52:55], v[166:169], v[182:185], v[52:55]
	v_mfma_f32_16x16x32_bf16 v[48:51], v[174:177], v[182:185], v[48:51]
	v_mfma_f32_16x16x32_bf16 v[36:39], v[166:169], v[190:193], v[36:39]
	v_mfma_f32_16x16x32_bf16 v[32:35], v[174:177], v[190:193], v[32:35]
	v_mfma_f32_16x16x32_bf16 v[20:23], v[166:169], v[198:201], v[20:23]
	v_mfma_f32_16x16x32_bf16 v[16:19], v[174:177], v[198:201], v[16:19]
	v_mfma_f32_16x16x32_bf16 v[4:7], v[166:169], v[208:211], v[4:7]
	v_mfma_f32_16x16x32_bf16 v[0:3], v[174:177], v[208:211], v[0:3]
	v_mfma_f32_16x16x32_bf16 v[52:55], v[170:173], v[186:189], v[52:55]
	v_mfma_f32_16x16x32_bf16 v[48:51], v[178:181], v[186:189], v[48:51]
	v_mfma_f32_16x16x32_bf16 v[36:39], v[170:173], v[194:197], v[36:39]
	v_mfma_f32_16x16x32_bf16 v[32:35], v[178:181], v[194:197], v[32:35]
	v_mfma_f32_16x16x32_bf16 v[20:23], v[170:173], v[202:205], v[20:23]
	v_mfma_f32_16x16x32_bf16 v[16:19], v[178:181], v[202:205], v[16:19]
	v_mfma_f32_16x16x32_bf16 v[4:7], v[170:173], v[226:229], v[4:7]
	v_mfma_f32_16x16x32_bf16 v[0:3], v[178:181], v[226:229], v[0:3]
	s_setprio 0
	s_barrier
	s_add_i32 s73, s73, 2
	s_add_u32 s12, s12, 0x100
	s_addc_u32 s13, s13, 0
	s_add_u32 s54, s54, 0x100
	s_addc_u32 s55, s55, 0
	s_cmp_gt_u32 s73, 13
	s_cbranch_scc0 .LBB0_396
	s_and_b64 vcc, exec, s[70:71]
	s_cbranch_vccz .LBB0_399
	s_barrier

.LBB0_401:
	s_cmp_lt_i32 s54, s49
	s_cselect_b32 s100, s25, 1.0
	s_cmp_lt_i32 s47, 2
	s_cselect_b64 s[30:31], -1, 0
	s_and_b64 s[30:31], s[30:31], s[64:65]
	s_lshl_b32 s1, s40, 8
	s_add_i32 s1, s1, s84
	s_waitcnt vmcnt(8)
	s_and_b64 vcc, exec, s[8:9]
	s_cbranch_vccz .Lmy_b16_noearly
	s_add_u32 s14, s76, 0x40080
	s_addc_u32 s15, s77, 0
	v_lshl_add_u64 v[152:153], s[14:15], 0, v[140:141]
	s_add_i32 m0, s41, 0xc000
	s_nop 0
	global_load_lds_dwordx4 v[152:153], off
	v_lshl_add_u64 v[152:153], s[14:15], 0, v[142:143]
	s_add_i32 m0, s41, 0xe000
	s_nop 0
	global_load_lds_dwordx4 v[152:153], off
.Lmy_b16_noearly:
	s_and_b64 vcc, exec, s[58:59]
	s_cbranch_vccz .Lmy_b16_plain
	s_lshr_b32 s75, s33, 11
	s_lshl_b32 s55, s75, 1
	s_sub_i32 s73, 13, s55
	s_lshr_b32 s10, s1, 13
	s_mul_i32 s10, s10, 3
	s_add_i32 s10, s10, s75
	s_mov_b32 s11, 0
	s_lshl_b64 s[10:11], s[10:11], 25
	s_add_u32 s10, s22, s10
	s_addc_u32 s11, s23, s11
	s_lshl_b32 s12, s33, 14
	s_and_b32 s12, s12, 0x1e00000
	s_add_u32 s10, s10, s12
	s_addc_u32 s11, s11, 0
	s_lshl_b32 s12, s85, 1
	s_add_u32 s10, s10, s12
	s_addc_u32 s11, s11, 0
	s_and_b32 s12, s1, 0x1fff
	s_lshr_b32 s12, s12, s55
	s_lshl_b32 s12, s12, 8
	s_add_u32 s10, s10, s12
	s_addc_u32 s11, s11, 0
	s_lshr_b32 s12, 0x1000, s55
	s_lshr_b32 s13, 0x8000, s55
	s_mov_b32 s14, 0x200000
	s_lshl_b32 s15, 1, s55
	s_add_i32 s15, s15, -1
	v_lshrrev_b32_e32 v157, 2, v224
	v_and_b32_e32 v144, s15, v157
	v_lshlrev_b32_e32 v144, s73, v144
	v_lshrrev_b32_e32 v145, s55, v157
	v_add_lshl_u32 v144, v144, v145, 8
	v_and_b32_e32 v145, 3, v224
	v_lshl_add_u32 v144, v145, 4, v144
	s_branch .Lmy_b16_addr
.Lmy_b16_plain:
	s_cmp_lt_i32 s1, s57
	s_cselect_b64 s[12:13], -1, 0
	s_or_b64 s[12:13], s[12:13], s[16:17]
	s_cmp_lg_u64 s[12:13], 0
	s_cselect_b32 s10, s28, s18
	s_cselect_b32 s11, s29, s19
	s_cselect_b32 s12, 0, s57
	s_sub_i32 s12, s1, s12
	s_mul_hi_u32 s15, s12, s24
	s_mul_i32 s14, s12, s24
	s_add_i32 s12, s33, s85
	s_add_u32 s14, s14, s12
	s_addc_u32 s15, s15, 0
	s_lshl_b64 s[14:15], s[14:15], 1
	s_add_u32 s10, s10, s14
	s_addc_u32 s11, s11, s15
	s_lshl_b32 s12, s24, 5
	s_lshl_b32 s13, s24, 8
	s_movk_i32 s14, 0x100
	v_lshrrev_b32_e32 v157, 2, v224
	v_mul_lo_u32 v144, v157, s24
	v_and_b32_e32 v145, 3, v224
	v_lshlrev_b32_e32 v145, 3, v145
	v_add_lshl_u32 v144, v144, v145, 1
.Lmy_b16_addr:
	v_and_b32_e32 v145, 3, v224
	v_lshlrev_b32_e32 v145, 6, v145
	v_and_or_b32 v145, v224, 60, v145
	s_add_u32 s28, s10, s14
	s_addc_u32 s29, s11, 0
	s_mul_i32 s15, s12, 3
	s_sub_i32 s13, s13, s15
	s_and_b64 vcc, exec, s[30:31]
	s_cbranch_vccnz .Lmy_b16_norm
	v_fmamk_f32 v158, v236, 0x3a800000, v207
	v_rsq_f32_e32 v158, v158
	s_nop 0
	v_mul_f32_e32 v158, s100, v158
	v_pk_mul_f32 v[126:127], v[126:127], v[158:159] op_sel_hi:[1,0]
	v_pk_mul_f32 v[128:129], v[128:129], v[158:159] op_sel_hi:[1,0]
	v_pk_mul_f32 v[122:123], v[122:123], v[158:159] op_sel_hi:[1,0]
	v_pk_mul_f32 v[124:125], v[124:125], v[158:159] op_sel_hi:[1,0]
	v_cvt_pk_bf16_f32 v146, v126, v127
	v_cvt_pk_bf16_f32 v147, v128, v129
	v_cvt_pk_bf16_f32 v148, v122, v123
	v_cvt_pk_bf16_f32 v149, v124, v125
	ds_bpermute_b32 v168, v145, v146
	ds_bpermute_b32 v169, v145, v147
	ds_bpermute_b32 v170, v145, v148
	ds_bpermute_b32 v171, v145, v149
	v_pk_mul_f32 v[118:119], v[118:119], v[158:159] op_sel_hi:[1,0]
	v_pk_mul_f32 v[120:121], v[120:121], v[158:159] op_sel_hi:[1,0]
	v_pk_mul_f32 v[114:115], v[114:115], v[158:159] op_sel_hi:[1,0]
	v_pk_mul_f32 v[116:117], v[116:117], v[158:159] op_sel_hi:[1,0]
	v_cvt_pk_bf16_f32 v150, v118, v119
	v_cvt_pk_bf16_f32 v151, v120, v121
	v_cvt_pk_bf16_f32 v152, v114, v115
	v_cvt_pk_bf16_f32 v153, v116, v117
	ds_bpermute_b32 v172, v145, v150
	ds_bpermute_b32 v173, v145, v151
	ds_bpermute_b32 v174, v145, v152
	ds_bpermute_b32 v175, v145, v153
	s_waitcnt lgkmcnt(4)
	global_store_dwordx4 v144, v[168:171], s[10:11]
	s_add_u32 s54, s10, s12
	s_addc_u32 s55, s11, 0
	s_add_u32 s80, s28, s12
	s_addc_u32 s81, s29, 0
	v_fmamk_f32 v158, v237, 0x3a800000, v207
	v_rsq_f32_e32 v158, v158
	s_nop 0
	v_mul_f32_e32 v158, s100, v158
	v_pk_mul_f32 v[110:111], v[110:111], v[158:159] op_sel_hi:[1,0]
	v_pk_mul_f32 v[112:113], v[112:113], v[158:159] op_sel_hi:[1,0]
	v_pk_mul_f32 v[106:107], v[106:107], v[158:159] op_sel_hi:[1,0]
	v_pk_mul_f32 v[108:109], v[108:109], v[158:159] op_sel_hi:[1,0]
	v_cvt_pk_bf16_f32 v146, v110, v111
	v_cvt_pk_bf16_f32 v147, v112, v113
	v_cvt_pk_bf16_f32 v148, v106, v107
	v_cvt_pk_bf16_f32 v149, v108, v109
	ds_bpermute_b32 v168, v145, v146
	ds_bpermute_b32 v169, v145, v147
	ds_bpermute_b32 v170, v145, v148
	ds_bpermute_b32 v171, v145, v149
	s_waitcnt lgkmcnt(4)
	global_store_dwordx4 v144, v[172:175], s[28:29]
	v_pk_mul_f32 v[102:103], v[102:103], v[158:159] op_sel_hi:[1,0]
	v_pk_mul_f32 v[104:105], v[104:105], v[158:159] op_sel_hi:[1,0]
	v_pk_mul_f32 v[96:97], v[96:97], v[158:159] op_sel_hi:[1,0]
	v_pk_mul_f32 v[98:99], v[98:99], v[158:159] op_sel_hi:[1,0]
	v_cvt_pk_bf16_f32 v150, v102, v103
	v_cvt_pk_bf16_f32 v151, v104, v105
	v_cvt_pk_bf16_f32 v152, v96, v97
	v_cvt_pk_bf16_f32 v153, v98, v99
	ds_bpermute_b32 v172, v145, v150
	ds_bpermute_b32 v173, v145, v151
	ds_bpermute_b32 v174, v145, v152
	ds_bpermute_b32 v175, v145, v153
	s_waitcnt lgkmcnt(4)
	global_store_dwordx4 v144, v[168:171], s[54:55]
	s_add_u32 s10, s54, s12
	s_addc_u32 s11, s55, 0
	s_add_u32 s28, s80, s12
	s_addc_u32 s29, s81, 0
	v_fmamk_f32 v158, v238, 0x3a800000, v207
	v_rsq_f32_e32 v158, v158
	s_nop 0
	v_mul_f32_e32 v158, s100, v158
	v_pk_mul_f32 v[92:93], v[92:93], v[158:159] op_sel_hi:[1,0]
	v_pk_mul_f32 v[94:95], v[94:95], v[158:159] op_sel_hi:[1,0]
	v_pk_mul_f32 v[88:89], v[88:89], v[158:159] op_sel_hi:[1,0]
	v_pk_mul_f32 v[90:91], v[90:91], v[158:159] op_sel_hi:[1,0]
	v_cvt_pk_bf16_f32 v146, v92, v93
	v_cvt_pk_bf16_f32 v147, v94, v95
	v_cvt_pk_bf16_f32 v148, v88, v89
	v_cvt_pk_bf16_f32 v149, v90, v91
	ds_bpermute_b32 v168, v145, v146
	ds_bpermute_b32 v169, v145, v147
	ds_bpermute_b32 v170, v145, v148
	ds_bpermute_b32 v171, v145, v149
	s_waitcnt lgkmcnt(4)
	global_store_dwordx4 v144, v[172:175], s[80:81]
	v_pk_mul_f32 v[84:85], v[84:85], v[158:159] op_sel_hi:[1,0]
	v_pk_mul_f32 v[86:87], v[86:87], v[158:159] op_sel_hi:[1,0]
	v_pk_mul_f32 v[80:81], v[80:81], v[158:159] op_sel_hi:[1,0]
	v_pk_mul_f32 v[82:83], v[82:83], v[158:159] op_sel_hi:[1,0]
	v_cvt_pk_bf16_f32 v150, v84, v85
	v_cvt_pk_bf16_f32 v151, v86, v87
	v_cvt_pk_bf16_f32 v152, v80, v81
	v_cvt_pk_bf16_f32 v153, v82, v83
	ds_bpermute_b32 v172, v145, v150
	ds_bpermute_b32 v173, v145, v151
	ds_bpermute_b32 v174, v145, v152
	ds_bpermute_b32 v175, v145, v153
	s_waitcnt lgkmcnt(4)
	global_store_dwordx4 v144, v[168:171], s[10:11]
	s_add_u32 s54, s10, s12
	s_addc_u32 s55, s11, 0
	s_add_u32 s80, s28, s12
	s_addc_u32 s81, s29, 0
	v_fmamk_f32 v158, v239, 0x3a800000, v207
	v_rsq_f32_e32 v158, v158
	s_nop 0
	v_mul_f32_e32 v158, s100, v158
	v_pk_mul_f32 v[76:77], v[76:77], v[158:159] op_sel_hi:[1,0]
	v_pk_mul_f32 v[78:79], v[78:79], v[158:159] op_sel_hi:[1,0]
	v_pk_mul_f32 v[72:73], v[72:73], v[158:159] op_sel_hi:[1,0]
	v_pk_mul_f32 v[74:75], v[74:75], v[158:159] op_sel_hi:[1,0]
	v_cvt_pk_bf16_f32 v146, v76, v77
	v_cvt_pk_bf16_f32 v147, v78, v79
	v_cvt_pk_bf16_f32 v148, v72, v73
	v_cvt_pk_bf16_f32 v149, v74, v75
	ds_bpermute_b32 v168, v145, v146
	ds_bpermute_b32 v169, v145, v147
	ds_bpermute_b32 v170, v145, v148
	ds_bpermute_b32 v171, v145, v149
	s_waitcnt lgkmcnt(4)
	global_store_dwordx4 v144, v[172:175], s[28:29]
	v_pk_mul_f32 v[68:69], v[68:69], v[158:159] op_sel_hi:[1,0]
	v_pk_mul_f32 v[70:71], v[70:71], v[158:159] op_sel_hi:[1,0]
	v_pk_mul_f32 v[64:65], v[64:65], v[158:159] op_sel_hi:[1,0]
	v_pk_mul_f32 v[66:67], v[66:67], v[158:159] op_sel_hi:[1,0]
	v_cvt_pk_bf16_f32 v150, v68, v69
	v_cvt_pk_bf16_f32 v151, v70, v71
	v_cvt_pk_bf16_f32 v152, v64, v65
	v_cvt_pk_bf16_f32 v153, v66, v67
	ds_bpermute_b32 v172, v145, v150
	ds_bpermute_b32 v173, v145, v151
	ds_bpermute_b32 v174, v145, v152
	ds_bpermute_b32 v175, v145, v153
	s_waitcnt lgkmcnt(4)
	global_store_dwordx4 v144, v[168:171], s[54:55]
	s_add_u32 s10, s54, s13
	s_addc_u32 s11, s55, 0
	s_add_u32 s28, s80, s13
	s_addc_u32 s29, s81, 0
	v_fmamk_f32 v158, v240, 0x3a800000, v207
	v_rsq_f32_e32 v158, v158
	s_nop 0
	v_mul_f32_e32 v158, s100, v158
	v_pk_mul_f32 v[60:61], v[60:61], v[158:159] op_sel_hi:[1,0]
	v_pk_mul_f32 v[62:63], v[62:63], v[158:159] op_sel_hi:[1,0]
	v_pk_mul_f32 v[56:57], v[56:57], v[158:159] op_sel_hi:[1,0]
	v_pk_mul_f32 v[58:59], v[58:59], v[158:159] op_sel_hi:[1,0]
	v_cvt_pk_bf16_f32 v146, v60, v61
	v_cvt_pk_bf16_f32 v147, v62, v63
	v_cvt_pk_bf16_f32 v148, v56, v57
	v_cvt_pk_bf16_f32 v149, v58, v59
	ds_bpermute_b32 v168, v145, v146
	ds_bpermute_b32 v169, v145, v147
	ds_bpermute_b32 v170, v145, v148
	ds_bpermute_b32 v171, v145, v149
	s_waitcnt lgkmcnt(4)
	global_store_dwordx4 v144, v[172:175], s[80:81]
	v_pk_mul_f32 v[52:53], v[52:53], v[158:159] op_sel_hi:[1,0]
	v_pk_mul_f32 v[54:55], v[54:55], v[158:159] op_sel_hi:[1,0]
	v_pk_mul_f32 v[48:49], v[48:49], v[158:159] op_sel_hi:[1,0]
	v_pk_mul_f32 v[50:51], v[50:51], v[158:159] op_sel_hi:[1,0]
	v_cvt_pk_bf16_f32 v150, v52, v53
	v_cvt_pk_bf16_f32 v151, v54, v55
	v_cvt_pk_bf16_f32 v152, v48, v49
	v_cvt_pk_bf16_f32 v153, v50, v51
	ds_bpermute_b32 v172, v145, v150
	ds_bpermute_b32 v173, v145, v151
	ds_bpermute_b32 v174, v145, v152
	ds_bpermute_b32 v175, v145, v153
	s_waitcnt lgkmcnt(4)
	global_store_dwordx4 v144, v[168:171], s[10:11]
	s_add_u32 s54, s10, s12
	s_addc_u32 s55, s11, 0
	s_add_u32 s80, s28, s12
	s_addc_u32 s81, s29, 0
	v_fmamk_f32 v158, v244, 0x3a800000, v207
	v_rsq_f32_e32 v158, v158
	s_nop 0
	v_mul_f32_e32 v158, s100, v158
	v_pk_mul_f32 v[44:45], v[44:45], v[158:159] op_sel_hi:[1,0]
	v_pk_mul_f32 v[46:47], v[46:47], v[158:159] op_sel_hi:[1,0]
	v_pk_mul_f32 v[40:41], v[40:41], v[158:159] op_sel_hi:[1,0]
	v_pk_mul_f32 v[42:43], v[42:43], v[158:159] op_sel_hi:[1,0]
	v_cvt_pk_bf16_f32 v146, v44, v45
	v_cvt_pk_bf16_f32 v147, v46, v47
	v_cvt_pk_bf16_f32 v148, v40, v41
	v_cvt_pk_bf16_f32 v149, v42, v43
	ds_bpermute_b32 v168, v145, v146
	ds_bpermute_b32 v169, v145, v147
	ds_bpermute_b32 v170, v145, v148
	ds_bpermute_b32 v171, v145, v149
	s_waitcnt lgkmcnt(4)
	global_store_dwordx4 v144, v[172:175], s[28:29]
	v_pk_mul_f32 v[36:37], v[36:37], v[158:159] op_sel_hi:[1,0]
	v_pk_mul_f32 v[38:39], v[38:39], v[158:159] op_sel_hi:[1,0]
	v_pk_mul_f32 v[32:33], v[32:33], v[158:159] op_sel_hi:[1,0]
	v_pk_mul_f32 v[34:35], v[34:35], v[158:159] op_sel_hi:[1,0]
	v_cvt_pk_bf16_f32 v150, v36, v37
	v_cvt_pk_bf16_f32 v151, v38, v39
	v_cvt_pk_bf16_f32 v152, v32, v33
	v_cvt_pk_bf16_f32 v153, v34, v35
	ds_bpermute_b32 v172, v145, v150
	ds_bpermute_b32 v173, v145, v151
	ds_bpermute_b32 v174, v145, v152
	ds_bpermute_b32 v175, v145, v153
	s_waitcnt lgkmcnt(4)
	global_store_dwordx4 v144, v[168:171], s[54:55]
	s_add_u32 s10, s54, s12
	s_addc_u32 s11, s55, 0
	s_add_u32 s28, s80, s12
	s_addc_u32 s29, s81, 0
	v_fmamk_f32 v158, v245, 0x3a800000, v207
	v_rsq_f32_e32 v158, v158
	s_nop 0
	v_mul_f32_e32 v158, s100, v158
	v_pk_mul_f32 v[28:29], v[28:29], v[158:159] op_sel_hi:[1,0]
	v_pk_mul_f32 v[30:31], v[30:31], v[158:159] op_sel_hi:[1,0]
	v_pk_mul_f32 v[24:25], v[24:25], v[158:159] op_sel_hi:[1,0]
	v_pk_mul_f32 v[26:27], v[26:27], v[158:159] op_sel_hi:[1,0]
	v_cvt_pk_bf16_f32 v146, v28, v29
	v_cvt_pk_bf16_f32 v147, v30, v31
	v_cvt_pk_bf16_f32 v148, v24, v25
	v_cvt_pk_bf16_f32 v149, v26, v27
	ds_bpermute_b32 v168, v145, v146
	ds_bpermute_b32 v169, v145, v147
	ds_bpermute_b32 v170, v145, v148
	ds_bpermute_b32 v171, v145, v149
	s_waitcnt lgkmcnt(4)
	global_store_dwordx4 v144, v[172:175], s[80:81]
	v_pk_mul_f32 v[20:21], v[20:21], v[158:159] op_sel_hi:[1,0]
	v_pk_mul_f32 v[22:23], v[22:23], v[158:159] op_sel_hi:[1,0]
	v_pk_mul_f32 v[16:17], v[16:17], v[158:159] op_sel_hi:[1,0]
	v_pk_mul_f32 v[18:19], v[18:19], v[158:159] op_sel_hi:[1,0]
	v_cvt_pk_bf16_f32 v150, v20, v21
	v_cvt_pk_bf16_f32 v151, v22, v23
	v_cvt_pk_bf16_f32 v152, v16, v17
	v_cvt_pk_bf16_f32 v153, v18, v19
	ds_bpermute_b32 v172, v145, v150
	ds_bpermute_b32 v173, v145, v151
	ds_bpermute_b32 v174, v145, v152
	ds_bpermute_b32 v175, v145, v153
	s_waitcnt lgkmcnt(4)
	global_store_dwordx4 v144, v[168:171], s[10:11]
	s_add_u32 s54, s10, s12
	s_addc_u32 s55, s11, 0
	s_add_u32 s80, s28, s12
	s_addc_u32 s81, s29, 0
	v_fmamk_f32 v158, v246, 0x3a800000, v207
	v_rsq_f32_e32 v158, v158
	s_nop 0
	v_mul_f32_e32 v158, s100, v158
	v_pk_mul_f32 v[12:13], v[12:13], v[158:159] op_sel_hi:[1,0]
	v_pk_mul_f32 v[14:15], v[14:15], v[158:159] op_sel_hi:[1,0]
	v_pk_mul_f32 v[8:9], v[8:9], v[158:159] op_sel_hi:[1,0]
	v_pk_mul_f32 v[10:11], v[10:11], v[158:159] op_sel_hi:[1,0]
	v_cvt_pk_bf16_f32 v146, v12, v13
	v_cvt_pk_bf16_f32 v147, v14, v15
	v_cvt_pk_bf16_f32 v148, v8, v9
	v_cvt_pk_bf16_f32 v149, v10, v11
	ds_bpermute_b32 v168, v145, v146
	ds_bpermute_b32 v169, v145, v147
	ds_bpermute_b32 v170, v145, v148
	ds_bpermute_b32 v171, v145, v149
	s_waitcnt lgkmcnt(4)
	global_store_dwordx4 v144, v[172:175], s[28:29]
	v_pk_mul_f32 v[4:5], v[4:5], v[158:159] op_sel_hi:[1,0]
	v_pk_mul_f32 v[6:7], v[6:7], v[158:159] op_sel_hi:[1,0]
	v_pk_mul_f32 v[0:1], v[0:1], v[158:159] op_sel_hi:[1,0]
	v_pk_mul_f32 v[2:3], v[2:3], v[158:159] op_sel_hi:[1,0]
	v_cvt_pk_bf16_f32 v150, v4, v5
	v_cvt_pk_bf16_f32 v151, v6, v7
	v_cvt_pk_bf16_f32 v152, v0, v1
	v_cvt_pk_bf16_f32 v153, v2, v3
	ds_bpermute_b32 v172, v145, v150
	ds_bpermute_b32 v173, v145, v151
	ds_bpermute_b32 v174, v145, v152
	ds_bpermute_b32 v175, v145, v153
	s_waitcnt lgkmcnt(4)
	global_store_dwordx4 v144, v[168:171], s[54:55]
	s_waitcnt lgkmcnt(0)
	global_store_dwordx4 v144, v[172:175], s[80:81]
	s_branch .Lmy_b16_done
.Lmy_b16_norm:
	v_mov_b32_e32 v164, 0
	v_mov_b32_e32 v165, 0
	v_mov_b32_e32 v166, 0
	v_mov_b32_e32 v167, 0
	v_fmamk_f32 v158, v236, 0x3a800000, v207
	v_rsq_f32_e32 v158, v158
	s_nop 0
	v_mul_f32_e32 v158, s100, v158
	v_pk_mul_f32 v[126:127], v[126:127], v[158:159] op_sel_hi:[1,0]
	v_pk_mul_f32 v[128:129], v[128:129], v[158:159] op_sel_hi:[1,0]
	v_pk_mul_f32 v[122:123], v[122:123], v[158:159] op_sel_hi:[1,0]
	v_pk_mul_f32 v[124:125], v[124:125], v[158:159] op_sel_hi:[1,0]
	v_cvt_pk_bf16_f32 v146, v126, v127
	v_cvt_pk_bf16_f32 v147, v128, v129
	v_cvt_pk_bf16_f32 v148, v122, v123
	v_cvt_pk_bf16_f32 v149, v124, v125
	ds_bpermute_b32 v168, v145, v146
	ds_bpermute_b32 v169, v145, v147
	ds_bpermute_b32 v170, v145, v148
	ds_bpermute_b32 v171, v145, v149
	v_pk_mul_f32 v[126:127], v[126:127], v[126:127]
	v_pk_mul_f32 v[128:129], v[128:129], v[128:129]
	v_pk_mul_f32 v[122:123], v[122:123], v[122:123]
	v_pk_mul_f32 v[124:125], v[124:125], v[124:125]
	v_add_f32_e32 v160, v126, v127
	v_add_f32_e32 v161, v128, v129
	v_add_f32_e32 v162, v122, v123
	v_add_f32_e32 v163, v124, v125
	v_add_f32_e32 v160, v160, v161
	v_add_f32_e32 v160, v162, v160
	v_add_f32_e32 v160, v163, v160
	ds_swizzle_b32 v161, v160 offset:swizzle(SWAP,16)
	s_waitcnt lgkmcnt(0)
	global_store_dwordx4 v144, v[168:171], s[10:11]
	v_add_f32_e32 v160, v160, v161
	v_mov_b32_e32 v161, v160
	s_nop 1
	v_permlane32_swap_b32_e32 v160, v161
	v_add_f32_e32 v160, v160, v161
	v_max_f32_e32 v164, v164, v160
	v_pk_mul_f32 v[118:119], v[118:119], v[158:159] op_sel_hi:[1,0]
	v_pk_mul_f32 v[120:121], v[120:121], v[158:159] op_sel_hi:[1,0]
	v_pk_mul_f32 v[114:115], v[114:115], v[158:159] op_sel_hi:[1,0]
	v_pk_mul_f32 v[116:117], v[116:117], v[158:159] op_sel_hi:[1,0]
	v_cvt_pk_bf16_f32 v150, v118, v119
	v_cvt_pk_bf16_f32 v151, v120, v121
	v_cvt_pk_bf16_f32 v152, v114, v115
	v_cvt_pk_bf16_f32 v153, v116, v117
	ds_bpermute_b32 v172, v145, v150
	ds_bpermute_b32 v173, v145, v151
	ds_bpermute_b32 v174, v145, v152
	ds_bpermute_b32 v175, v145, v153
	v_pk_mul_f32 v[118:119], v[118:119], v[118:119]
	v_pk_mul_f32 v[120:121], v[120:121], v[120:121]
	v_pk_mul_f32 v[114:115], v[114:115], v[114:115]
	v_pk_mul_f32 v[116:117], v[116:117], v[116:117]
	v_add_f32_e32 v160, v118, v119
	v_add_f32_e32 v161, v120, v121
	v_add_f32_e32 v162, v114, v115
	v_add_f32_e32 v163, v116, v117
	v_add_f32_e32 v160, v160, v161
	v_add_f32_e32 v160, v162, v160
	v_add_f32_e32 v160, v163, v160
	ds_swizzle_b32 v161, v160 offset:swizzle(SWAP,16)
	s_waitcnt lgkmcnt(0)
	global_store_dwordx4 v144, v[172:175], s[28:29]
	v_add_f32_e32 v160, v160, v161
	v_mov_b32_e32 v161, v160
	s_nop 1
	v_permlane32_swap_b32_e32 v160, v161
	v_add_f32_e32 v160, v160, v161
	v_max_f32_e32 v165, v165, v160
	s_add_u32 s54, s10, s12
	s_addc_u32 s55, s11, 0
	s_add_u32 s80, s28, s12
	s_addc_u32 s81, s29, 0
	v_fmamk_f32 v158, v237, 0x3a800000, v207
	v_rsq_f32_e32 v158, v158
	s_nop 0
	v_mul_f32_e32 v158, s100, v158
	v_pk_mul_f32 v[110:111], v[110:111], v[158:159] op_sel_hi:[1,0]
	v_pk_mul_f32 v[112:113], v[112:113], v[158:159] op_sel_hi:[1,0]
	v_pk_mul_f32 v[106:107], v[106:107], v[158:159] op_sel_hi:[1,0]
	v_pk_mul_f32 v[108:109], v[108:109], v[158:159] op_sel_hi:[1,0]
	v_cvt_pk_bf16_f32 v146, v110, v111
	v_cvt_pk_bf16_f32 v147, v112, v113
	v_cvt_pk_bf16_f32 v148, v106, v107
	v_cvt_pk_bf16_f32 v149, v108, v109
	ds_bpermute_b32 v168, v145, v146
	ds_bpermute_b32 v169, v145, v147
	ds_bpermute_b32 v170, v145, v148
	ds_bpermute_b32 v171, v145, v149
	v_pk_mul_f32 v[110:111], v[110:111], v[110:111]
	v_pk_mul_f32 v[112:113], v[112:113], v[112:113]
	v_pk_mul_f32 v[106:107], v[106:107], v[106:107]
	v_pk_mul_f32 v[108:109], v[108:109], v[108:109]
	v_add_f32_e32 v160, v110, v111
	v_add_f32_e32 v161, v112, v113
	v_add_f32_e32 v162, v106, v107
	v_add_f32_e32 v163, v108, v109
	v_add_f32_e32 v160, v160, v161
	v_add_f32_e32 v160, v162, v160
	v_add_f32_e32 v160, v163, v160
	ds_swizzle_b32 v161, v160 offset:swizzle(SWAP,16)
	s_waitcnt lgkmcnt(0)
	global_store_dwordx4 v144, v[168:171], s[54:55]
	v_add_f32_e32 v160, v160, v161
	v_mov_b32_e32 v161, v160
	s_nop 1
	v_permlane32_swap_b32_e32 v160, v161
	v_add_f32_e32 v160, v160, v161
	v_max_f32_e32 v164, v164, v160
	v_pk_mul_f32 v[102:103], v[102:103], v[158:159] op_sel_hi:[1,0]
	v_pk_mul_f32 v[104:105], v[104:105], v[158:159] op_sel_hi:[1,0]
	v_pk_mul_f32 v[96:97], v[96:97], v[158:159] op_sel_hi:[1,0]
	v_pk_mul_f32 v[98:99], v[98:99], v[158:159] op_sel_hi:[1,0]
	v_cvt_pk_bf16_f32 v150, v102, v103
	v_cvt_pk_bf16_f32 v151, v104, v105
	v_cvt_pk_bf16_f32 v152, v96, v97
	v_cvt_pk_bf16_f32 v153, v98, v99
	ds_bpermute_b32 v172, v145, v150
	ds_bpermute_b32 v173, v145, v151
	ds_bpermute_b32 v174, v145, v152
	ds_bpermute_b32 v175, v145, v153
	v_pk_mul_f32 v[102:103], v[102:103], v[102:103]
	v_pk_mul_f32 v[104:105], v[104:105], v[104:105]
	v_pk_mul_f32 v[96:97], v[96:97], v[96:97]
	v_pk_mul_f32 v[98:99], v[98:99], v[98:99]
	v_add_f32_e32 v160, v102, v103
	v_add_f32_e32 v161, v104, v105
	v_add_f32_e32 v162, v96, v97
	v_add_f32_e32 v163, v98, v99
	v_add_f32_e32 v160, v160, v161
	v_add_f32_e32 v160, v162, v160
	v_add_f32_e32 v160, v163, v160
	ds_swizzle_b32 v161, v160 offset:swizzle(SWAP,16)
	s_waitcnt lgkmcnt(0)
	global_store_dwordx4 v144, v[172:175], s[80:81]
	v_add_f32_e32 v160, v160, v161
	v_mov_b32_e32 v161, v160
	s_nop 1
	v_permlane32_swap_b32_e32 v160, v161
	v_add_f32_e32 v160, v160, v161
	v_max_f32_e32 v165, v165, v160
	s_add_u32 s10, s54, s12
	s_addc_u32 s11, s55, 0
	s_add_u32 s28, s80, s12
	s_addc_u32 s29, s81, 0
	v_fmamk_f32 v158, v238, 0x3a800000, v207
	v_rsq_f32_e32 v158, v158
	s_nop 0
	v_mul_f32_e32 v158, s100, v158
	v_pk_mul_f32 v[92:93], v[92:93], v[158:159] op_sel_hi:[1,0]
	v_pk_mul_f32 v[94:95], v[94:95], v[158:159] op_sel_hi:[1,0]
	v_pk_mul_f32 v[88:89], v[88:89], v[158:159] op_sel_hi:[1,0]
	v_pk_mul_f32 v[90:91], v[90:91], v[158:159] op_sel_hi:[1,0]
	v_cvt_pk_bf16_f32 v146, v92, v93
	v_cvt_pk_bf16_f32 v147, v94, v95
	v_cvt_pk_bf16_f32 v148, v88, v89
	v_cvt_pk_bf16_f32 v149, v90, v91
	ds_bpermute_b32 v168, v145, v146
	ds_bpermute_b32 v169, v145, v147
	ds_bpermute_b32 v170, v145, v148
	ds_bpermute_b32 v171, v145, v149
	v_pk_mul_f32 v[92:93], v[92:93], v[92:93]
	v_pk_mul_f32 v[94:95], v[94:95], v[94:95]
	v_pk_mul_f32 v[88:89], v[88:89], v[88:89]
	v_pk_mul_f32 v[90:91], v[90:91], v[90:91]
	v_add_f32_e32 v160, v92, v93
	v_add_f32_e32 v161, v94, v95
	v_add_f32_e32 v162, v88, v89
	v_add_f32_e32 v163, v90, v91
	v_add_f32_e32 v160, v160, v161
	v_add_f32_e32 v160, v162, v160
	v_add_f32_e32 v160, v163, v160
	ds_swizzle_b32 v161, v160 offset:swizzle(SWAP,16)
	s_waitcnt lgkmcnt(0)
	global_store_dwordx4 v144, v[168:171], s[10:11]
	v_add_f32_e32 v160, v160, v161
	v_mov_b32_e32 v161, v160
	s_nop 1
	v_permlane32_swap_b32_e32 v160, v161
	v_add_f32_e32 v160, v160, v161
	v_max_f32_e32 v164, v164, v160
	v_pk_mul_f32 v[84:85], v[84:85], v[158:159] op_sel_hi:[1,0]
	v_pk_mul_f32 v[86:87], v[86:87], v[158:159] op_sel_hi:[1,0]
	v_pk_mul_f32 v[80:81], v[80:81], v[158:159] op_sel_hi:[1,0]
	v_pk_mul_f32 v[82:83], v[82:83], v[158:159] op_sel_hi:[1,0]
	v_cvt_pk_bf16_f32 v150, v84, v85
	v_cvt_pk_bf16_f32 v151, v86, v87
	v_cvt_pk_bf16_f32 v152, v80, v81
	v_cvt_pk_bf16_f32 v153, v82, v83
	ds_bpermute_b32 v172, v145, v150
	ds_bpermute_b32 v173, v145, v151
	ds_bpermute_b32 v174, v145, v152
	ds_bpermute_b32 v175, v145, v153
	v_pk_mul_f32 v[84:85], v[84:85], v[84:85]
	v_pk_mul_f32 v[86:87], v[86:87], v[86:87]
	v_pk_mul_f32 v[80:81], v[80:81], v[80:81]
	v_pk_mul_f32 v[82:83], v[82:83], v[82:83]
	v_add_f32_e32 v160, v84, v85
	v_add_f32_e32 v161, v86, v87
	v_add_f32_e32 v162, v80, v81
	v_add_f32_e32 v163, v82, v83
	v_add_f32_e32 v160, v160, v161
	v_add_f32_e32 v160, v162, v160
	v_add_f32_e32 v160, v163, v160
	ds_swizzle_b32 v161, v160 offset:swizzle(SWAP,16)
	s_waitcnt lgkmcnt(0)
	global_store_dwordx4 v144, v[172:175], s[28:29]
	v_add_f32_e32 v160, v160, v161
	v_mov_b32_e32 v161, v160
	s_nop 1
	v_permlane32_swap_b32_e32 v160, v161
	v_add_f32_e32 v160, v160, v161
	v_max_f32_e32 v165, v165, v160
	s_add_u32 s54, s10, s12
	s_addc_u32 s55, s11, 0
	s_add_u32 s80, s28, s12
	s_addc_u32 s81, s29, 0
	v_fmamk_f32 v158, v239, 0x3a800000, v207
	v_rsq_f32_e32 v158, v158
	s_nop 0
	v_mul_f32_e32 v158, s100, v158
	v_pk_mul_f32 v[76:77], v[76:77], v[158:159] op_sel_hi:[1,0]
	v_pk_mul_f32 v[78:79], v[78:79], v[158:159] op_sel_hi:[1,0]
	v_pk_mul_f32 v[72:73], v[72:73], v[158:159] op_sel_hi:[1,0]
	v_pk_mul_f32 v[74:75], v[74:75], v[158:159] op_sel_hi:[1,0]
	v_cvt_pk_bf16_f32 v146, v76, v77
	v_cvt_pk_bf16_f32 v147, v78, v79
	v_cvt_pk_bf16_f32 v148, v72, v73
	v_cvt_pk_bf16_f32 v149, v74, v75
	ds_bpermute_b32 v168, v145, v146
	ds_bpermute_b32 v169, v145, v147
	ds_bpermute_b32 v170, v145, v148
	ds_bpermute_b32 v171, v145, v149
	v_pk_mul_f32 v[76:77], v[76:77], v[76:77]
	v_pk_mul_f32 v[78:79], v[78:79], v[78:79]
	v_pk_mul_f32 v[72:73], v[72:73], v[72:73]
	v_pk_mul_f32 v[74:75], v[74:75], v[74:75]
	v_add_f32_e32 v160, v76, v77
	v_add_f32_e32 v161, v78, v79
	v_add_f32_e32 v162, v72, v73
	v_add_f32_e32 v163, v74, v75
	v_add_f32_e32 v160, v160, v161
	v_add_f32_e32 v160, v162, v160
	v_add_f32_e32 v160, v163, v160
	ds_swizzle_b32 v161, v160 offset:swizzle(SWAP,16)
	s_waitcnt lgkmcnt(0)
	global_store_dwordx4 v144, v[168:171], s[54:55]
	v_add_f32_e32 v160, v160, v161
	v_mov_b32_e32 v161, v160
	s_nop 1
	v_permlane32_swap_b32_e32 v160, v161
	v_add_f32_e32 v160, v160, v161
	v_max_f32_e32 v164, v164, v160
	v_pk_mul_f32 v[68:69], v[68:69], v[158:159] op_sel_hi:[1,0]
	v_pk_mul_f32 v[70:71], v[70:71], v[158:159] op_sel_hi:[1,0]
	v_pk_mul_f32 v[64:65], v[64:65], v[158:159] op_sel_hi:[1,0]
	v_pk_mul_f32 v[66:67], v[66:67], v[158:159] op_sel_hi:[1,0]
	v_cvt_pk_bf16_f32 v150, v68, v69
	v_cvt_pk_bf16_f32 v151, v70, v71
	v_cvt_pk_bf16_f32 v152, v64, v65
	v_cvt_pk_bf16_f32 v153, v66, v67
	ds_bpermute_b32 v172, v145, v150
	ds_bpermute_b32 v173, v145, v151
	ds_bpermute_b32 v174, v145, v152
	ds_bpermute_b32 v175, v145, v153
	v_pk_mul_f32 v[68:69], v[68:69], v[68:69]
	v_pk_mul_f32 v[70:71], v[70:71], v[70:71]
	v_pk_mul_f32 v[64:65], v[64:65], v[64:65]
	v_pk_mul_f32 v[66:67], v[66:67], v[66:67]
	v_add_f32_e32 v160, v68, v69
	v_add_f32_e32 v161, v70, v71
	v_add_f32_e32 v162, v64, v65
	v_add_f32_e32 v163, v66, v67
	v_add_f32_e32 v160, v160, v161
	v_add_f32_e32 v160, v162, v160
	v_add_f32_e32 v160, v163, v160
	ds_swizzle_b32 v161, v160 offset:swizzle(SWAP,16)
	s_waitcnt lgkmcnt(0)
	global_store_dwordx4 v144, v[172:175], s[80:81]
	v_add_f32_e32 v160, v160, v161
	v_mov_b32_e32 v161, v160
	s_nop 1
	v_permlane32_swap_b32_e32 v160, v161
	v_add_f32_e32 v160, v160, v161
	v_max_f32_e32 v165, v165, v160
	s_add_u32 s10, s54, s13
	s_addc_u32 s11, s55, 0
	s_add_u32 s28, s80, s13
	s_addc_u32 s29, s81, 0
	v_fmamk_f32 v158, v240, 0x3a800000, v207
	v_rsq_f32_e32 v158, v158
	s_nop 0
	v_mul_f32_e32 v158, s100, v158
	v_pk_mul_f32 v[60:61], v[60:61], v[158:159] op_sel_hi:[1,0]
	v_pk_mul_f32 v[62:63], v[62:63], v[158:159] op_sel_hi:[1,0]
	v_pk_mul_f32 v[56:57], v[56:57], v[158:159] op_sel_hi:[1,0]
	v_pk_mul_f32 v[58:59], v[58:59], v[158:159] op_sel_hi:[1,0]
	v_cvt_pk_bf16_f32 v146, v60, v61
	v_cvt_pk_bf16_f32 v147, v62, v63
	v_cvt_pk_bf16_f32 v148, v56, v57
	v_cvt_pk_bf16_f32 v149, v58, v59
	ds_bpermute_b32 v168, v145, v146
	ds_bpermute_b32 v169, v145, v147
	ds_bpermute_b32 v170, v145, v148
	ds_bpermute_b32 v171, v145, v149
	v_pk_mul_f32 v[60:61], v[60:61], v[60:61]
	v_pk_mul_f32 v[62:63], v[62:63], v[62:63]
	v_pk_mul_f32 v[56:57], v[56:57], v[56:57]
	v_pk_mul_f32 v[58:59], v[58:59], v[58:59]
	v_add_f32_e32 v160, v60, v61
	v_add_f32_e32 v161, v62, v63
	v_add_f32_e32 v162, v56, v57
	v_add_f32_e32 v163, v58, v59
	v_add_f32_e32 v160, v160, v161
	v_add_f32_e32 v160, v162, v160
	v_add_f32_e32 v160, v163, v160
	ds_swizzle_b32 v161, v160 offset:swizzle(SWAP,16)
	s_waitcnt lgkmcnt(0)
	global_store_dwordx4 v144, v[168:171], s[10:11]
	v_add_f32_e32 v160, v160, v161
	v_mov_b32_e32 v161, v160
	s_nop 1
	v_permlane32_swap_b32_e32 v160, v161
	v_add_f32_e32 v160, v160, v161
	v_max_f32_e32 v166, v166, v160
	v_pk_mul_f32 v[52:53], v[52:53], v[158:159] op_sel_hi:[1,0]
	v_pk_mul_f32 v[54:55], v[54:55], v[158:159] op_sel_hi:[1,0]
	v_pk_mul_f32 v[48:49], v[48:49], v[158:159] op_sel_hi:[1,0]
	v_pk_mul_f32 v[50:51], v[50:51], v[158:159] op_sel_hi:[1,0]
	v_cvt_pk_bf16_f32 v150, v52, v53
	v_cvt_pk_bf16_f32 v151, v54, v55
	v_cvt_pk_bf16_f32 v152, v48, v49
	v_cvt_pk_bf16_f32 v153, v50, v51
	ds_bpermute_b32 v172, v145, v150
	ds_bpermute_b32 v173, v145, v151
	ds_bpermute_b32 v174, v145, v152
	ds_bpermute_b32 v175, v145, v153
	v_pk_mul_f32 v[52:53], v[52:53], v[52:53]
	v_pk_mul_f32 v[54:55], v[54:55], v[54:55]
	v_pk_mul_f32 v[48:49], v[48:49], v[48:49]
	v_pk_mul_f32 v[50:51], v[50:51], v[50:51]
	v_add_f32_e32 v160, v52, v53
	v_add_f32_e32 v161, v54, v55
	v_add_f32_e32 v162, v48, v49
	v_add_f32_e32 v163, v50, v51
	v_add_f32_e32 v160, v160, v161
	v_add_f32_e32 v160, v162, v160
	v_add_f32_e32 v160, v163, v160
	ds_swizzle_b32 v161, v160 offset:swizzle(SWAP,16)
	s_waitcnt lgkmcnt(0)
	global_store_dwordx4 v144, v[172:175], s[28:29]
	v_add_f32_e32 v160, v160, v161
	v_mov_b32_e32 v161, v160
	s_nop 1
	v_permlane32_swap_b32_e32 v160, v161
	v_add_f32_e32 v160, v160, v161
	v_max_f32_e32 v167, v167, v160
	s_add_u32 s54, s10, s12
	s_addc_u32 s55, s11, 0
	s_add_u32 s80, s28, s12
	s_addc_u32 s81, s29, 0
	v_fmamk_f32 v158, v244, 0x3a800000, v207
	v_rsq_f32_e32 v158, v158
	s_nop 0
	v_mul_f32_e32 v158, s100, v158
	v_pk_mul_f32 v[44:45], v[44:45], v[158:159] op_sel_hi:[1,0]
	v_pk_mul_f32 v[46:47], v[46:47], v[158:159] op_sel_hi:[1,0]
	v_pk_mul_f32 v[40:41], v[40:41], v[158:159] op_sel_hi:[1,0]
	v_pk_mul_f32 v[42:43], v[42:43], v[158:159] op_sel_hi:[1,0]
	v_cvt_pk_bf16_f32 v146, v44, v45
	v_cvt_pk_bf16_f32 v147, v46, v47
	v_cvt_pk_bf16_f32 v148, v40, v41
	v_cvt_pk_bf16_f32 v149, v42, v43
	ds_bpermute_b32 v168, v145, v146
	ds_bpermute_b32 v169, v145, v147
	ds_bpermute_b32 v170, v145, v148
	ds_bpermute_b32 v171, v145, v149
	v_pk_mul_f32 v[44:45], v[44:45], v[44:45]
	v_pk_mul_f32 v[46:47], v[46:47], v[46:47]
	v_pk_mul_f32 v[40:41], v[40:41], v[40:41]
	v_pk_mul_f32 v[42:43], v[42:43], v[42:43]
	v_add_f32_e32 v160, v44, v45
	v_add_f32_e32 v161, v46, v47
	v_add_f32_e32 v162, v40, v41
	v_add_f32_e32 v163, v42, v43
	v_add_f32_e32 v160, v160, v161
	v_add_f32_e32 v160, v162, v160
	v_add_f32_e32 v160, v163, v160
	ds_swizzle_b32 v161, v160 offset:swizzle(SWAP,16)
	s_waitcnt lgkmcnt(0)
	global_store_dwordx4 v144, v[168:171], s[54:55]
	v_add_f32_e32 v160, v160, v161
	v_mov_b32_e32 v161, v160
	s_nop 1
	v_permlane32_swap_b32_e32 v160, v161
	v_add_f32_e32 v160, v160, v161
	v_max_f32_e32 v166, v166, v160
	v_pk_mul_f32 v[36:37], v[36:37], v[158:159] op_sel_hi:[1,0]
	v_pk_mul_f32 v[38:39], v[38:39], v[158:159] op_sel_hi:[1,0]
	v_pk_mul_f32 v[32:33], v[32:33], v[158:159] op_sel_hi:[1,0]
	v_pk_mul_f32 v[34:35], v[34:35], v[158:159] op_sel_hi:[1,0]
	v_cvt_pk_bf16_f32 v150, v36, v37
	v_cvt_pk_bf16_f32 v151, v38, v39
	v_cvt_pk_bf16_f32 v152, v32, v33
	v_cvt_pk_bf16_f32 v153, v34, v35
	ds_bpermute_b32 v172, v145, v150
	ds_bpermute_b32 v173, v145, v151
	ds_bpermute_b32 v174, v145, v152
	ds_bpermute_b32 v175, v145, v153
	v_pk_mul_f32 v[36:37], v[36:37], v[36:37]
	v_pk_mul_f32 v[38:39], v[38:39], v[38:39]
	v_pk_mul_f32 v[32:33], v[32:33], v[32:33]
	v_pk_mul_f32 v[34:35], v[34:35], v[34:35]
	v_add_f32_e32 v160, v36, v37
	v_add_f32_e32 v161, v38, v39
	v_add_f32_e32 v162, v32, v33
	v_add_f32_e32 v163, v34, v35
	v_add_f32_e32 v160, v160, v161
	v_add_f32_e32 v160, v162, v160
	v_add_f32_e32 v160, v163, v160
	ds_swizzle_b32 v161, v160 offset:swizzle(SWAP,16)
	s_waitcnt lgkmcnt(0)
	global_store_dwordx4 v144, v[172:175], s[80:81]
	v_add_f32_e32 v160, v160, v161
	v_mov_b32_e32 v161, v160
	s_nop 1
	v_permlane32_swap_b32_e32 v160, v161
	v_add_f32_e32 v160, v160, v161
	v_max_f32_e32 v167, v167, v160
	s_add_u32 s10, s54, s12
	s_addc_u32 s11, s55, 0
	s_add_u32 s28, s80, s12
	s_addc_u32 s29, s81, 0
	v_fmamk_f32 v158, v245, 0x3a800000, v207
	v_rsq_f32_e32 v158, v158
	s_nop 0
	v_mul_f32_e32 v158, s100, v158
	v_pk_mul_f32 v[28:29], v[28:29], v[158:159] op_sel_hi:[1,0]
	v_pk_mul_f32 v[30:31], v[30:31], v[158:159] op_sel_hi:[1,0]
	v_pk_mul_f32 v[24:25], v[24:25], v[158:159] op_sel_hi:[1,0]
	v_pk_mul_f32 v[26:27], v[26:27], v[158:159] op_sel_hi:[1,0]
	v_cvt_pk_bf16_f32 v146, v28, v29
	v_cvt_pk_bf16_f32 v147, v30, v31
	v_cvt_pk_bf16_f32 v148, v24, v25
	v_cvt_pk_bf16_f32 v149, v26, v27
	ds_bpermute_b32 v168, v145, v146
	ds_bpermute_b32 v169, v145, v147
	ds_bpermute_b32 v170, v145, v148
	ds_bpermute_b32 v171, v145, v149
	v_pk_mul_f32 v[28:29], v[28:29], v[28:29]
	v_pk_mul_f32 v[30:31], v[30:31], v[30:31]
	v_pk_mul_f32 v[24:25], v[24:25], v[24:25]
	v_pk_mul_f32 v[26:27], v[26:27], v[26:27]
	v_add_f32_e32 v160, v28, v29
	v_add_f32_e32 v161, v30, v31
	v_add_f32_e32 v162, v24, v25
	v_add_f32_e32 v163, v26, v27
	v_add_f32_e32 v160, v160, v161
	v_add_f32_e32 v160, v162, v160
	v_add_f32_e32 v160, v163, v160
	ds_swizzle_b32 v161, v160 offset:swizzle(SWAP,16)
	s_waitcnt lgkmcnt(0)
	global_store_dwordx4 v144, v[168:171], s[10:11]
	v_add_f32_e32 v160, v160, v161
	v_mov_b32_e32 v161, v160
	s_nop 1
	v_permlane32_swap_b32_e32 v160, v161
	v_add_f32_e32 v160, v160, v161
	v_max_f32_e32 v166, v166, v160
	v_pk_mul_f32 v[20:21], v[20:21], v[158:159] op_sel_hi:[1,0]
	v_pk_mul_f32 v[22:23], v[22:23], v[158:159] op_sel_hi:[1,0]
	v_pk_mul_f32 v[16:17], v[16:17], v[158:159] op_sel_hi:[1,0]
	v_pk_mul_f32 v[18:19], v[18:19], v[158:159] op_sel_hi:[1,0]
	v_cvt_pk_bf16_f32 v150, v20, v21
	v_cvt_pk_bf16_f32 v151, v22, v23
	v_cvt_pk_bf16_f32 v152, v16, v17
	v_cvt_pk_bf16_f32 v153, v18, v19
	ds_bpermute_b32 v172, v145, v150
	ds_bpermute_b32 v173, v145, v151
	ds_bpermute_b32 v174, v145, v152
	ds_bpermute_b32 v175, v145, v153
	v_pk_mul_f32 v[20:21], v[20:21], v[20:21]
	v_pk_mul_f32 v[22:23], v[22:23], v[22:23]
	v_pk_mul_f32 v[16:17], v[16:17], v[16:17]
	v_pk_mul_f32 v[18:19], v[18:19], v[18:19]
	v_add_f32_e32 v160, v20, v21
	v_add_f32_e32 v161, v22, v23
	v_add_f32_e32 v162, v16, v17
	v_add_f32_e32 v163, v18, v19
	v_add_f32_e32 v160, v160, v161
	v_add_f32_e32 v160, v162, v160
	v_add_f32_e32 v160, v163, v160
	ds_swizzle_b32 v161, v160 offset:swizzle(SWAP,16)
	s_waitcnt lgkmcnt(0)
	global_store_dwordx4 v144, v[172:175], s[28:29]
	v_add_f32_e32 v160, v160, v161
	v_mov_b32_e32 v161, v160
	s_nop 1
	v_permlane32_swap_b32_e32 v160, v161
	v_add_f32_e32 v160, v160, v161
	v_max_f32_e32 v167, v167, v160
	s_add_u32 s54, s10, s12
	s_addc_u32 s55, s11, 0
	s_add_u32 s80, s28, s12
	s_addc_u32 s81, s29, 0
	v_fmamk_f32 v158, v246, 0x3a800000, v207
	v_rsq_f32_e32 v158, v158
	s_nop 0
	v_mul_f32_e32 v158, s100, v158
	v_pk_mul_f32 v[12:13], v[12:13], v[158:159] op_sel_hi:[1,0]
	v_pk_mul_f32 v[14:15], v[14:15], v[158:159] op_sel_hi:[1,0]
	v_pk_mul_f32 v[8:9], v[8:9], v[158:159] op_sel_hi:[1,0]
	v_pk_mul_f32 v[10:11], v[10:11], v[158:159] op_sel_hi:[1,0]
	v_cvt_pk_bf16_f32 v146, v12, v13
	v_cvt_pk_bf16_f32 v147, v14, v15
	v_cvt_pk_bf16_f32 v148, v8, v9
	v_cvt_pk_bf16_f32 v149, v10, v11
	ds_bpermute_b32 v168, v145, v146
	ds_bpermute_b32 v169, v145, v147
	ds_bpermute_b32 v170, v145, v148
	ds_bpermute_b32 v171, v145, v149
	v_pk_mul_f32 v[12:13], v[12:13], v[12:13]
	v_pk_mul_f32 v[14:15], v[14:15], v[14:15]
	v_pk_mul_f32 v[8:9], v[8:9], v[8:9]
	v_pk_mul_f32 v[10:11], v[10:11], v[10:11]
	v_add_f32_e32 v160, v12, v13
	v_add_f32_e32 v161, v14, v15
	v_add_f32_e32 v162, v8, v9
	v_add_f32_e32 v163, v10, v11
	v_add_f32_e32 v160, v160, v161
	v_add_f32_e32 v160, v162, v160
	v_add_f32_e32 v160, v163, v160
	ds_swizzle_b32 v161, v160 offset:swizzle(SWAP,16)
	s_waitcnt lgkmcnt(0)
	global_store_dwordx4 v144, v[168:171], s[54:55]
	v_add_f32_e32 v160, v160, v161
	v_mov_b32_e32 v161, v160
	s_nop 1
	v_permlane32_swap_b32_e32 v160, v161
	v_add_f32_e32 v160, v160, v161
	v_max_f32_e32 v166, v166, v160
	v_pk_mul_f32 v[4:5], v[4:5], v[158:159] op_sel_hi:[1,0]
	v_pk_mul_f32 v[6:7], v[6:7], v[158:159] op_sel_hi:[1,0]
	v_pk_mul_f32 v[0:1], v[0:1], v[158:159] op_sel_hi:[1,0]
	v_pk_mul_f32 v[2:3], v[2:3], v[158:159] op_sel_hi:[1,0]
	v_cvt_pk_bf16_f32 v150, v4, v5
	v_cvt_pk_bf16_f32 v151, v6, v7
	v_cvt_pk_bf16_f32 v152, v0, v1
	v_cvt_pk_bf16_f32 v153, v2, v3
	ds_bpermute_b32 v172, v145, v150
	ds_bpermute_b32 v173, v145, v151
	ds_bpermute_b32 v174, v145, v152
	ds_bpermute_b32 v175, v145, v153
	v_pk_mul_f32 v[4:5], v[4:5], v[4:5]
	v_pk_mul_f32 v[6:7], v[6:7], v[6:7]
	v_pk_mul_f32 v[0:1], v[0:1], v[0:1]
	v_pk_mul_f32 v[2:3], v[2:3], v[2:3]
	v_add_f32_e32 v160, v4, v5
	v_add_f32_e32 v161, v6, v7
	v_add_f32_e32 v162, v0, v1
	v_add_f32_e32 v163, v2, v3
	v_add_f32_e32 v160, v160, v161
	v_add_f32_e32 v160, v162, v160
	v_add_f32_e32 v160, v163, v160
	ds_swizzle_b32 v161, v160 offset:swizzle(SWAP,16)
	s_waitcnt lgkmcnt(0)
	global_store_dwordx4 v144, v[172:175], s[80:81]
	v_add_f32_e32 v160, v160, v161
	v_mov_b32_e32 v161, v160
	s_nop 1
	v_permlane32_swap_b32_e32 v160, v161
	v_add_f32_e32 v160, v160, v161
	v_max_f32_e32 v167, v167, v160
	ds_swizzle_b32 v160, v164 offset:swizzle(SWAP,1)
	s_waitcnt lgkmcnt(0)
	v_max_f32_e32 v164, v164, v160
	ds_swizzle_b32 v160, v164 offset:swizzle(SWAP,2)
	s_waitcnt lgkmcnt(0)
	v_max_f32_e32 v164, v164, v160
	ds_swizzle_b32 v160, v164 offset:swizzle(SWAP,4)
	s_waitcnt lgkmcnt(0)
	v_max_f32_e32 v164, v164, v160
	ds_swizzle_b32 v160, v164 offset:swizzle(SWAP,8)
	s_waitcnt lgkmcnt(0)
	v_max_f32_e32 v164, v164, v160
	ds_swizzle_b32 v160, v165 offset:swizzle(SWAP,1)
	s_waitcnt lgkmcnt(0)
	v_max_f32_e32 v165, v165, v160
	ds_swizzle_b32 v160, v165 offset:swizzle(SWAP,2)
	s_waitcnt lgkmcnt(0)
	v_max_f32_e32 v165, v165, v160
	ds_swizzle_b32 v160, v165 offset:swizzle(SWAP,4)
	s_waitcnt lgkmcnt(0)
	v_max_f32_e32 v165, v165, v160
	ds_swizzle_b32 v160, v165 offset:swizzle(SWAP,8)
	s_waitcnt lgkmcnt(0)
	v_max_f32_e32 v165, v165, v160
	ds_swizzle_b32 v160, v166 offset:swizzle(SWAP,1)
	s_waitcnt lgkmcnt(0)
	v_max_f32_e32 v166, v166, v160
	ds_swizzle_b32 v160, v166 offset:swizzle(SWAP,2)
	s_waitcnt lgkmcnt(0)
	v_max_f32_e32 v166, v166, v160
	ds_swizzle_b32 v160, v166 offset:swizzle(SWAP,4)
	s_waitcnt lgkmcnt(0)
	v_max_f32_e32 v166, v166, v160
	ds_swizzle_b32 v160, v166 offset:swizzle(SWAP,8)
	s_waitcnt lgkmcnt(0)
	v_max_f32_e32 v166, v166, v160
	ds_swizzle_b32 v160, v167 offset:swizzle(SWAP,1)
	s_waitcnt lgkmcnt(0)
	v_max_f32_e32 v167, v167, v160
	ds_swizzle_b32 v160, v167 offset:swizzle(SWAP,2)
	s_waitcnt lgkmcnt(0)
	v_max_f32_e32 v167, v167, v160
	ds_swizzle_b32 v160, v167 offset:swizzle(SWAP,4)
	s_waitcnt lgkmcnt(0)
	v_max_f32_e32 v167, v167, v160
	ds_swizzle_b32 v160, v167 offset:swizzle(SWAP,8)
	s_waitcnt lgkmcnt(0)
	v_max_f32_e32 v167, v167, v160
	s_ashr_i32 s11, s40, 5
	s_lshl_b32 s14, s47, 3
	s_add_i32 s14, s14, s11
	s_lshl_b32 s14, s14, 10
	s_ashr_i32 s15, s33, 6
	s_add_i32 s15, s15, s94
	s_lshl_b32 s15, s15, 6
	s_add_i32 s14, s14, s15
	s_lshl_b32 s15, s40, 1
	s_and_b32 s15, s15, 62
	s_or_b32 s14, s14, s15
	s_lshl_b32 s14, s14, 3
	s_add_u32 s14, s95, s14
	s_addc_u32 s15, s98, 0
	s_and_saveexec_b64 s[12:13], s[6:7]
	s_cbranch_execz .Lmy_b16_noatom
	global_atomic_umax v101, v164, s[14:15]
	global_atomic_umax v101, v165, s[14:15] offset:1024
	global_atomic_umax v101, v166, s[14:15] offset:8
	global_atomic_umax v101, v167, s[14:15] offset:1032

.Lmy_b16_done:
.LBB0_477:
	s_andn2_b64 vcc, exec, s[8:9]
	s_mov_b64 s[8:9], -1
	s_cbranch_vccnz .LBB0_392
	s_andn2_b64 vcc, exec, s[42:43]
	s_cbranch_vccnz .LBB0_391
	s_barrier
	s_branch .LBB0_391

	.amdhsa_kernel _Z8yoco_fwd4Args
		.amdhsa_group_segment_fixed_size 0
		.amdhsa_private_segment_fixed_size 0
		.amdhsa_kernarg_size 384
		.amdhsa_user_sgpr_count 2
		.amdhsa_user_sgpr_dispatch_ptr 0
		.amdhsa_user_sgpr_queue_ptr 0
		.amdhsa_user_sgpr_kernarg_segment_ptr 1
		.amdhsa_user_sgpr_dispatch_id 0
		.amdhsa_user_sgpr_kernarg_preload_length 0
		.amdhsa_user_sgpr_kernarg_preload_offset 0
		.amdhsa_user_sgpr_private_segment_size 0
		.amdhsa_uses_dynamic_stack 0
		.amdhsa_enable_private_segment 0
		.amdhsa_system_sgpr_workgroup_id_x 1
		.amdhsa_system_sgpr_workgroup_id_y 0
		.amdhsa_system_sgpr_workgroup_id_z 0
		.amdhsa_system_sgpr_workgroup_info 0
		.amdhsa_system_vgpr_workitem_id 2
		.amdhsa_next_free_vgpr 248
		.amdhsa_next_free_sgpr 102
		.amdhsa_accum_offset 248
		.amdhsa_reserve_vcc 1
		.amdhsa_float_round_mode_32 0
		.amdhsa_float_round_mode_16_64 0
		.amdhsa_float_denorm_mode_32 3
		.amdhsa_float_denorm_mode_16_64 3
		.amdhsa_dx10_clamp 1
		.amdhsa_ieee_mode 1
		.amdhsa_fp16_overflow 0
		.amdhsa_tg_split 0
		.amdhsa_exception_fp_ieee_invalid_op 0
		.amdhsa_exception_fp_denorm_src 0
		.amdhsa_exception_fp_ieee_div_zero 0
		.amdhsa_exception_fp_ieee_overflow 0
		.amdhsa_exception_fp_ieee_underflow 0
		.amdhsa_exception_fp_ieee_inexact 0
		.amdhsa_exception_int_div_zero 0
	.end_amdhsa_kernel

amdhsa.kernels:
  - .agpr_count:     0
    .args:
      - .offset:         0
        .size:           128
        .value_kind:     by_value
      - .offset:         128
        .size:           4
        .value_kind:     hidden_block_count_x
      - .offset:         132
        .size:           4
        .value_kind:     hidden_block_count_y
      - .offset:         136
        .size:           4
        .value_kind:     hidden_block_count_z
      - .offset:         140
        .size:           2
        .value_kind:     hidden_group_size_x
      - .offset:         142
        .size:           2
        .value_kind:     hidden_group_size_y
      - .offset:         144
        .size:           2
        .value_kind:     hidden_group_size_z
      - .offset:         146
        .size:           2
        .value_kind:     hidden_remainder_x
      - .offset:         148
        .size:           2
        .value_kind:     hidden_remainder_y
      - .offset:         150
        .size:           2
        .value_kind:     hidden_remainder_z
      - .offset:         168
        .size:           8
        .value_kind:     hidden_global_offset_x
      - .offset:         176
        .size:           8
        .value_kind:     hidden_global_offset_y
      - .offset:         184
        .size:           8
        .value_kind:     hidden_global_offset_z
      - .offset:         192
        .size:           2
        .value_kind:     hidden_grid_dims
      - .offset:         216
        .size:           8
        .value_kind:     hidden_multigrid_sync_arg
      - .offset:         248
        .size:           4
        .value_kind:     hidden_dynamic_lds_size
    .group_segment_fixed_size: 0
    .kernarg_segment_align: 8
    .kernarg_segment_size: 384
    .language:       OpenCL C
    .language_version:
      - 2
      - 0
    .max_flat_workgroup_size: 512
    .name:           _Z8yoco_fwd4Args
    .private_segment_fixed_size: 0
    .sgpr_count:     108
    .sgpr_spill_count: 204
    .symbol:         _Z8yoco_fwd4Args.kd
    .uniform_work_group_size: 1
    .uses_dynamic_stack: false
    .vgpr_count:     248
    .vgpr_spill_count: 0
    .wavefront_size: 64
